# EpiQ rope rows: table loads two row blocks ahead (two staging register sets) instead of one
# baseline (speedup 1.0000x reference)
.LBB0_847:
	v_mov_b32_e32 v145, v165
	v_and_b32_e32 v157, 64, v219
	v_lshrrev_b32_e32 v146, 31, v145
	v_add_u32_e32 v148, v145, v146
	v_and_b32_e32 v146, 0x3ffffffe, v148
	v_sub_u32_e32 v146, v145, v146
	v_lshlrev_b32_e32 v146, 2, v146
	v_ashrrev_i32_e32 v147, 31, v146
	v_lshl_add_u64 v[150:151], v[146:147], 2, s[18:19]
	v_xor_b32_e32 v146, 1, v219
	v_add_u32_e32 v147, 64, v157
	s_lshl_b32 s0, s34, 8
	v_cmp_lt_i32_e32 vcc, v146, v147
	s_add_i32 s0, s0, s52
	v_ashrrev_i32_e32 v156, 1, v148
	v_cndmask_b32_e32 v146, v219, v146, vcc
	v_lshlrev_b32_e32 v158, 2, v146
	v_and_b32_e32 v146, 0xffffff80, v148
	v_and_or_b32 v147, v156, 63, s0
	v_add_u32_e32 v152, v147, v146
	v_ashrrev_i32_e32 v153, 31, v152
	v_lshlrev_b64 v[146:147], 5, v[152:153]
	v_lshl_add_u64 v[146:147], v[150:151], 0, v[146:147]
	v_add_co_u32_e32 v178, vcc, 0x1000, v146
	v_addc_co_u32_e32 v179, vcc, 0, v147, vcc
	global_load_dwordx4 v[160:163], v[146:147], off offset:1024
	global_load_dwordx4 v[174:177], v[178:179], off
	global_load_dwordx4 v[194:197], v[178:179], off offset:1024
	global_load_dwordx4 v[146:149], v[146:147], off
	v_and_b32_e32 v145, 15, v145
	v_lshlrev_b32_e32 v145, 3, v145
	v_lshl_or_b32 v145, v157, 2, v145
	s_cmp_gt_i32 s62, 3
	v_or_b32_e32 v144, s0, v137
	s_cselect_b64 s[34:35], -1, 0
	s_mov_b64 s[16:17], -1
	v_lshlrev_b32_e32 v180, 1, v136
	s_waitcnt vmcnt(0)
	v_mov_b32_e32 v154, v147
	v_mov_b32_e32 v155, v148
	v_mov_b32_e32 v147, v149
	v_pk_add_f32 v[146:147], v[154:155], v[146:147]
	s_nop 0
	v_add_f32_e32 v146, v146, v147
	s_nop 1
	s_waitcnt lgkmcnt(0)
	v_add_f32_dpp v146, v146, v146 quad_perm:[1,0,3,2] row_mask:0xf bank_mask:0xf
	v_fmamk_f32 v146, v146, 0x3b2aaaab, v200
	v_rsq_f32_e32 v153, v146
	v_add_u32_e32 v146, 32, v156
	v_lshlrev_b32_e32 v147, 1, v146
	v_and_b32_e32 v147, 0xffffff80, v147
	v_and_or_b32 v146, v146, 63, s0
	v_add_u32_e32 v146, v146, v147
	v_ashrrev_i32_e32 v147, 31, v146
	v_lshlrev_b64 v[146:147], 5, v[146:147]
	v_lshl_add_u64 v[146:147], v[150:151], 0, v[146:147]
	ds_bpermute_b32 v173, v145, v153 offset:128
	s_waitcnt vmcnt(0)
	v_mov_b32_e32 v146, v160
	v_mov_b32_e32 v147, v161
	v_mov_b32_e32 v148, v162
	v_mov_b32_e32 v149, v163
	v_add_f32_e32 v146, v146, v147
	v_add_f32_e32 v147, v148, v149
	v_add_f32_e32 v146, v146, v147
	s_nop 1
	s_waitcnt lgkmcnt(0)
	v_add_f32_dpp v146, v146, v146 quad_perm:[1,0,3,2] row_mask:0xf bank_mask:0xf
	v_fmamk_f32 v146, v146, 0x3b2aaaab, v200
	v_rsq_f32_e32 v154, v146
	v_add_u32_e32 v146, 0x80, v152
	v_ashrrev_i32_e32 v147, 31, v146
	v_lshlrev_b64 v[146:147], 5, v[146:147]
	v_lshl_add_u64 v[146:147], v[150:151], 0, v[146:147]
	ds_bpermute_b32 v172, v145, v154
	ds_bpermute_b32 v171, v145, v154 offset:128
	s_waitcnt vmcnt(0)
	v_mov_b32_e32 v146, v174
	v_mov_b32_e32 v147, v175
	v_mov_b32_e32 v148, v176
	v_mov_b32_e32 v149, v177
	v_add_f32_e32 v146, v146, v147
	v_add_f32_e32 v147, v148, v149
	v_add_f32_e32 v146, v146, v147
	s_nop 1
	s_waitcnt lgkmcnt(0)
	v_add_f32_dpp v146, v146, v146 quad_perm:[1,0,3,2] row_mask:0xf bank_mask:0xf
	v_fmamk_f32 v146, v146, 0x3b2aaaab, v200
	v_rsq_f32_e32 v152, v146
	v_add_u32_e32 v146, 0x60, v156
	v_lshlrev_b32_e32 v147, 1, v146
	v_and_b32_e32 v147, 0xffffff80, v147
	v_and_or_b32 v146, v146, 63, s0
	v_add_u32_e32 v146, v146, v147
	v_ashrrev_i32_e32 v147, 31, v146
	v_lshlrev_b64 v[146:147], 5, v[146:147]
	v_lshl_add_u64 v[146:147], v[150:151], 0, v[146:147]
	ds_bpermute_b32 v170, v145, v152
	ds_bpermute_b32 v169, v145, v152 offset:128
	s_lshl_b32 s0, s62, 2
	s_add_i32 s0, s58, s0
	s_mulk_i32 s0, 0xc0
	s_ashr_i32 s1, s0, 31
	s_cmp_lt_i32 s62, 4
	s_waitcnt vmcnt(0)
	v_mov_b32_e32 v146, v194
	v_mov_b32_e32 v147, v195
	v_mov_b32_e32 v148, v196
	v_mov_b32_e32 v149, v197
	v_add_f32_e32 v146, v146, v147
	v_add_f32_e32 v147, v148, v149
	v_add_f32_e32 v146, v146, v147
	s_nop 1
	s_waitcnt lgkmcnt(0)
	v_add_f32_dpp v146, v146, v146 quad_perm:[1,0,3,2] row_mask:0xf bank_mask:0xf
	v_fmamk_f32 v146, v146, 0x3b2aaaab, v200
	v_rsq_f32_e32 v146, v146
	ds_bpermute_b32 v147, v145, v153
	ds_bpermute_b32 v168, v145, v146
	ds_bpermute_b32 v167, v145, v146 offset:128
	s_waitcnt lgkmcnt(2)
	v_mul_f32_e32 v146, 0x3dd53b94, v147
	v_mov_b32_e32 v147, v146
	v_pk_mul_f32 v[126:127], v[126:127], v[146:147] op_sel_hi:[1,0]
	v_pk_mul_f32 v[124:125], v[124:125], v[146:147] op_sel_hi:[1,0]
	v_ashrrev_i32_e32 v145, 31, v144
	v_pk_mul_f32 v[116:117], v[116:117], v[146:147]
	v_pk_mul_f32 v[120:121], v[120:121], v[146:147]
	v_pk_mul_f32 v[112:113], v[112:113], v[146:147]
	s_cbranch_scc1 .LBB0_849
	v_lshlrev_b64 v[148:149], 8, v[144:145]
	v_lshl_add_u64 v[152:153], v[138:139], 0, v[148:149]
	global_load_dwordx4 v[156:159], v[152:153], off offset:32
	global_load_dwordx4 v[174:177], v[152:153], off offset:48
	global_load_dwordx4 v[148:151], v[152:153], off
	global_load_dwordx4 v[160:163], v[152:153], off offset:16
	v_mov_b32_e32 v147, v146
	v_pk_mul_f32 v[178:179], v[118:119], v[146:147]
	s_mov_b64 s[16:17], 0
	s_waitcnt vmcnt(3)
	v_mov_b32_e32 v198, v157
	v_mov_b32_e32 v199, v159
	s_waitcnt vmcnt(1)
	v_mov_b32_e32 v196, v149
	s_waitcnt vmcnt(0)
	v_or_b32_e32 v202, 16, v144
	v_ashrrev_i32_e32 v203, 31, v202
	v_lshlrev_b64 v[202:203], 8, v[202:203]
	v_lshl_add_u64 v[202:203], v[138:139], 0, v[202:203]
	global_load_dwordx4 v[224:227], v[202:203], off offset:32
	global_load_dwordx4 v[228:231], v[202:203], off offset:48
	global_load_dwordx4 v[232:235], v[202:203], off
	global_load_dwordx4 v[236:239], v[202:203], off offset:16
	v_or_b32_e32 v202, 32, v144
	v_ashrrev_i32_e32 v203, 31, v202
	v_lshlrev_b64 v[202:203], 8, v[202:203]
	v_lshl_add_u64 v[202:203], v[138:139], 0, v[202:203]
	global_load_dwordx4 v[206:209], v[202:203], off offset:32
	global_load_dwordx4 v[210:213], v[202:203], off offset:48
	global_load_dwordx4 v[214:217], v[202:203], off
	global_load_dwordx4 v[220:223], v[202:203], off offset:16
	v_mov_b32_e32 v194, v161
	v_mov_b32_e32 v195, v163
	v_pk_mul_f32 v[152:153], v[178:179], v[194:195]
	v_mov_b32_e32 v197, v151
	v_mov_b32_e32 v161, v162
	v_mov_b32_e32 v149, v150
	v_pk_mul_f32 v[154:155], v[116:117], v[196:197]
	v_pk_fma_f32 v[152:153], v[126:127], v[160:161], v[152:153] neg_lo:[0,0,1] neg_hi:[0,0,1]
	v_pk_mul_f32 v[150:151], v[178:179], v[160:161]
	v_pk_mul_f32 v[160:161], v[116:117], v[148:149]
	v_pk_fma_f32 v[154:155], v[124:125], v[148:149], v[154:155] neg_lo:[0,0,1] neg_hi:[0,0,1]
	v_pk_fma_f32 v[148:149], v[126:127], v[194:195], v[150:151]
	v_pk_fma_f32 v[150:151], v[124:125], v[196:197], v[160:161]
	v_pk_mul_f32 v[194:195], v[114:115], v[146:147]
	v_mov_b32_e32 v196, v175
	v_mov_b32_e32 v197, v177
	v_pk_mul_f32 v[178:179], v[122:123], v[146:147]
	v_pk_mul_f32 v[160:161], v[194:195], v[196:197]
	v_mov_b32_e32 v175, v176
	v_mov_b32_e32 v157, v158
	v_pk_mul_f32 v[162:163], v[112:113], v[198:199]
	v_pk_fma_f32 v[160:161], v[178:179], v[174:175], v[160:161] neg_lo:[0,0,1] neg_hi:[0,0,1]
	v_pk_mul_f32 v[158:159], v[194:195], v[174:175]
	v_pk_mul_f32 v[174:175], v[112:113], v[156:157]
	v_pk_fma_f32 v[162:163], v[120:121], v[156:157], v[162:163] neg_lo:[0,0,1] neg_hi:[0,0,1]
	v_pk_fma_f32 v[156:157], v[178:179], v[196:197], v[158:159]
	v_pk_fma_f32 v[158:159], v[120:121], v[198:199], v[174:175]
	v_mov_b64_e32 v[174:175], s[20:21]
	v_mad_i64_i32 v[174:175], s[10:11], v144, s50, v[174:175]
	v_lshl_add_u64 v[174:175], s[0:1], 1, v[174:175]
	v_lshl_add_u64 v[178:179], v[174:175], 0, v[180:181]
	v_cvt_pk_bf16_f32 v174, v154, v155
	v_cvt_pk_bf16_f32 v175, v152, v153
	v_cvt_pk_bf16_f32 v176, v162, v163
	v_cvt_pk_bf16_f32 v177, v160, v161
	v_cvt_pk_bf16_f32 v150, v150, v151
	v_cvt_pk_bf16_f32 v151, v148, v149
	v_cvt_pk_bf16_f32 v152, v158, v159
	v_cvt_pk_bf16_f32 v153, v156, v157
	global_store_dwordx4 v[178:179], v[174:177], off offset:256
	global_store_dwordx4 v[178:179], v[150:153], off offset:320

.LBB0_851:
	v_mul_f32_e32 v112, 0x3dd53b94, v173
	s_nop 0
	v_or_b32_e32 v114, 16, v144
	v_mov_b32_e32 v113, v112
	v_cndmask_b32_e64 v116, 0, 1, s[34:35]
	v_pk_mul_f32 v[110:111], v[110:111], v[112:113] op_sel_hi:[1,0]
	v_pk_mul_f32 v[108:109], v[108:109], v[112:113] op_sel_hi:[1,0]
	v_ashrrev_i32_e32 v115, 31, v114
	s_mov_b64 s[10:11], -1
	v_cmp_ne_u32_e64 s[42:43], 1, v116
	s_andn2_b64 vcc, exec, s[34:35]
	v_pk_mul_f32 v[100:101], v[100:101], v[112:113]
	v_pk_mul_f32 v[104:105], v[104:105], v[112:113]
	v_pk_mul_f32 v[96:97], v[96:97], v[112:113]
	s_cbranch_vccnz .LBB0_853
	v_lshlrev_b64 v[116:117], 8, v[114:115]
	v_lshl_add_u64 v[120:121], v[138:139], 0, v[116:117]
	v_mov_b32_e32 v113, v112
	v_pk_mul_f32 v[154:155], v[102:103], v[112:113]
	s_waitcnt vmcnt(6)
	v_mov_b32_e32 v124, v224
	v_mov_b32_e32 v125, v225
	v_mov_b32_e32 v126, v226
	v_mov_b32_e32 v127, v227
	v_mov_b32_e32 v150, v228
	v_mov_b32_e32 v151, v229
	v_mov_b32_e32 v152, v230
	v_mov_b32_e32 v153, v231
	v_mov_b32_e32 v116, v232
	v_mov_b32_e32 v117, v233
	v_mov_b32_e32 v118, v234
	v_mov_b32_e32 v119, v235
	v_mov_b32_e32 v146, v236
	v_mov_b32_e32 v147, v237
	v_mov_b32_e32 v148, v238
	v_mov_b32_e32 v149, v239
	v_or_b32_e32 v202, 48, v144
	v_ashrrev_i32_e32 v203, 31, v202
	v_lshlrev_b64 v[202:203], 8, v[202:203]
	v_lshl_add_u64 v[202:203], v[138:139], 0, v[202:203]
	global_load_dwordx4 v[224:227], v[202:203], off offset:32
	global_load_dwordx4 v[228:231], v[202:203], off offset:48
	global_load_dwordx4 v[232:235], v[202:203], off
	global_load_dwordx4 v[236:239], v[202:203], off offset:16
	v_mov_b32_e32 v160, v125
	v_mov_b32_e32 v161, v127
	v_mov_b32_e32 v158, v117
	v_mov_b32_e32 v156, v147
	v_mov_b32_e32 v157, v149
	v_pk_mul_f32 v[120:121], v[154:155], v[156:157]
	v_mov_b32_e32 v159, v119
	v_mov_b32_e32 v147, v148
	v_mov_b32_e32 v117, v118
	v_pk_mul_f32 v[122:123], v[100:101], v[158:159]
	v_pk_fma_f32 v[120:121], v[110:111], v[146:147], v[120:121] neg_lo:[0,0,1] neg_hi:[0,0,1]
	v_pk_mul_f32 v[118:119], v[154:155], v[146:147]
	v_pk_mul_f32 v[146:147], v[100:101], v[116:117]
	v_pk_fma_f32 v[122:123], v[108:109], v[116:117], v[122:123] neg_lo:[0,0,1] neg_hi:[0,0,1]
	v_pk_fma_f32 v[116:117], v[110:111], v[156:157], v[118:119]
	v_pk_fma_f32 v[118:119], v[108:109], v[158:159], v[146:147]
	v_pk_mul_f32 v[156:157], v[98:99], v[112:113]
	v_mov_b32_e32 v158, v151
	v_mov_b32_e32 v159, v153
	v_pk_mul_f32 v[154:155], v[106:107], v[112:113]
	v_pk_mul_f32 v[146:147], v[156:157], v[158:159]
	v_mov_b32_e32 v151, v152
	v_mov_b32_e32 v125, v126
	v_pk_mul_f32 v[148:149], v[96:97], v[160:161]
	v_pk_fma_f32 v[146:147], v[154:155], v[150:151], v[146:147] neg_lo:[0,0,1] neg_hi:[0,0,1]
	v_pk_mul_f32 v[126:127], v[156:157], v[150:151]
	v_pk_mul_f32 v[150:151], v[96:97], v[124:125]
	v_pk_fma_f32 v[148:149], v[104:105], v[124:125], v[148:149] neg_lo:[0,0,1] neg_hi:[0,0,1]
	v_pk_fma_f32 v[124:125], v[154:155], v[158:159], v[126:127]
	v_pk_fma_f32 v[126:127], v[104:105], v[160:161], v[150:151]
	v_mov_b64_e32 v[150:151], s[20:21]
	v_mad_i64_i32 v[150:151], s[10:11], v114, s50, v[150:151]
	v_lshl_add_u64 v[150:151], s[0:1], 1, v[150:151]
	v_lshl_add_u64 v[154:155], v[150:151], 0, v[180:181]
	v_cvt_pk_bf16_f32 v150, v122, v123
	v_cvt_pk_bf16_f32 v151, v120, v121
	v_cvt_pk_bf16_f32 v152, v148, v149
	v_cvt_pk_bf16_f32 v153, v146, v147
	v_cvt_pk_bf16_f32 v118, v118, v119
	v_cvt_pk_bf16_f32 v119, v116, v117
	v_cvt_pk_bf16_f32 v120, v126, v127
	v_cvt_pk_bf16_f32 v121, v124, v125
	s_mov_b64 s[10:11], 0
	global_store_dwordx4 v[154:155], v[150:153], off offset:256
	global_store_dwordx4 v[154:155], v[118:121], off offset:320

.LBB0_855:
	v_mul_f32_e32 v96, 0x3dd53b94, v172
	s_nop 0
	v_or_b32_e32 v98, 32, v144
	v_mov_b32_e32 v97, v96
	v_pk_mul_f32 v[94:95], v[94:95], v[96:97] op_sel_hi:[1,0]
	v_pk_mul_f32 v[92:93], v[92:93], v[96:97] op_sel_hi:[1,0]
	v_ashrrev_i32_e32 v99, 31, v98
	s_mov_b64 s[10:11], -1
	s_and_b64 vcc, exec, s[42:43]
	v_pk_mul_f32 v[84:85], v[84:85], v[96:97]
	v_pk_mul_f32 v[88:89], v[88:89], v[96:97]
	v_pk_mul_f32 v[80:81], v[80:81], v[96:97]
	s_cbranch_vccnz .LBB0_857
	v_lshlrev_b64 v[100:101], 8, v[98:99]
	v_lshl_add_u64 v[104:105], v[138:139], 0, v[100:101]
	v_mov_b32_e32 v97, v96
	v_pk_mul_f32 v[120:121], v[86:87], v[96:97]
	s_waitcnt vmcnt(8)
	v_mov_b32_e32 v108, v206
	v_mov_b32_e32 v109, v207
	v_mov_b32_e32 v110, v208
	v_mov_b32_e32 v111, v209
	v_mov_b32_e32 v116, v210
	v_mov_b32_e32 v117, v211
	v_mov_b32_e32 v118, v212
	v_mov_b32_e32 v119, v213
	v_mov_b32_e32 v100, v214
	v_mov_b32_e32 v101, v215
	v_mov_b32_e32 v102, v216
	v_mov_b32_e32 v103, v217
	v_mov_b32_e32 v112, v220
	v_mov_b32_e32 v113, v221
	v_mov_b32_e32 v114, v222
	v_mov_b32_e32 v115, v223
	v_add_u32_e32 v202, 0x80, v144
	v_ashrrev_i32_e32 v203, 31, v202
	v_lshlrev_b64 v[202:203], 8, v[202:203]
	v_lshl_add_u64 v[202:203], v[138:139], 0, v[202:203]
	global_load_dwordx4 v[206:209], v[202:203], off offset:32
	global_load_dwordx4 v[210:213], v[202:203], off offset:48
	global_load_dwordx4 v[214:217], v[202:203], off
	global_load_dwordx4 v[220:223], v[202:203], off offset:16
	v_mov_b32_e32 v126, v109
	v_mov_b32_e32 v127, v111
	v_mov_b32_e32 v124, v101
	v_mov_b32_e32 v122, v113
	v_mov_b32_e32 v123, v115
	v_pk_mul_f32 v[104:105], v[120:121], v[122:123]
	v_mov_b32_e32 v125, v103
	v_mov_b32_e32 v113, v114
	v_mov_b32_e32 v101, v102
	v_pk_mul_f32 v[106:107], v[84:85], v[124:125]
	v_pk_fma_f32 v[104:105], v[94:95], v[112:113], v[104:105] neg_lo:[0,0,1] neg_hi:[0,0,1]
	v_pk_mul_f32 v[102:103], v[120:121], v[112:113]
	v_pk_mul_f32 v[112:113], v[84:85], v[100:101]
	v_pk_fma_f32 v[106:107], v[92:93], v[100:101], v[106:107] neg_lo:[0,0,1] neg_hi:[0,0,1]
	v_pk_fma_f32 v[100:101], v[94:95], v[122:123], v[102:103]
	v_pk_fma_f32 v[102:103], v[92:93], v[124:125], v[112:113]
	v_pk_mul_f32 v[122:123], v[82:83], v[96:97]
	v_mov_b32_e32 v124, v117
	v_mov_b32_e32 v125, v119
	v_pk_mul_f32 v[120:121], v[90:91], v[96:97]
	v_pk_mul_f32 v[112:113], v[122:123], v[124:125]
	v_mov_b32_e32 v117, v118
	v_mov_b32_e32 v109, v110
	v_pk_mul_f32 v[114:115], v[80:81], v[126:127]
	v_pk_fma_f32 v[112:113], v[120:121], v[116:117], v[112:113] neg_lo:[0,0,1] neg_hi:[0,0,1]
	v_pk_mul_f32 v[110:111], v[122:123], v[116:117]
	v_pk_mul_f32 v[116:117], v[80:81], v[108:109]
	v_pk_fma_f32 v[114:115], v[88:89], v[108:109], v[114:115] neg_lo:[0,0,1] neg_hi:[0,0,1]
	v_pk_fma_f32 v[108:109], v[120:121], v[124:125], v[110:111]
	v_pk_fma_f32 v[110:111], v[88:89], v[126:127], v[116:117]
	v_mov_b64_e32 v[116:117], s[20:21]
	v_mad_i64_i32 v[116:117], s[10:11], v98, s50, v[116:117]
	v_lshl_add_u64 v[116:117], s[0:1], 1, v[116:117]
	v_lshl_add_u64 v[120:121], v[116:117], 0, v[180:181]
	v_cvt_pk_bf16_f32 v116, v106, v107
	v_cvt_pk_bf16_f32 v117, v104, v105
	v_cvt_pk_bf16_f32 v118, v114, v115
	v_cvt_pk_bf16_f32 v119, v112, v113
	v_cvt_pk_bf16_f32 v102, v102, v103
	v_cvt_pk_bf16_f32 v103, v100, v101
	v_cvt_pk_bf16_f32 v104, v110, v111
	v_cvt_pk_bf16_f32 v105, v108, v109
	s_mov_b64 s[10:11], 0
	global_store_dwordx4 v[120:121], v[116:119], off offset:256
	global_store_dwordx4 v[120:121], v[102:105], off offset:320

.LBB0_859:
	v_mul_f32_e32 v80, 0x3dd53b94, v171
	s_nop 0
	v_or_b32_e32 v82, 48, v144
	v_mov_b32_e32 v81, v80
	v_pk_mul_f32 v[78:79], v[78:79], v[80:81] op_sel_hi:[1,0]
	v_pk_mul_f32 v[76:77], v[76:77], v[80:81] op_sel_hi:[1,0]
	v_ashrrev_i32_e32 v83, 31, v82
	s_mov_b64 s[10:11], -1
	s_and_b64 vcc, exec, s[42:43]
	v_pk_mul_f32 v[68:69], v[68:69], v[80:81]
	v_pk_mul_f32 v[72:73], v[72:73], v[80:81]
	v_pk_mul_f32 v[64:65], v[64:65], v[80:81]
	s_cbranch_vccnz .LBB0_861
	v_lshlrev_b64 v[84:85], 8, v[82:83]
	v_lshl_add_u64 v[88:89], v[138:139], 0, v[84:85]
	v_mov_b32_e32 v81, v80
	v_pk_mul_f32 v[104:105], v[70:71], v[80:81]
	s_waitcnt vmcnt(8)
	v_mov_b32_e32 v92, v224
	v_mov_b32_e32 v93, v225
	v_mov_b32_e32 v94, v226
	v_mov_b32_e32 v95, v227
	v_mov_b32_e32 v100, v228
	v_mov_b32_e32 v101, v229
	v_mov_b32_e32 v102, v230
	v_mov_b32_e32 v103, v231
	v_mov_b32_e32 v84, v232
	v_mov_b32_e32 v85, v233
	v_mov_b32_e32 v86, v234
	v_mov_b32_e32 v87, v235
	v_mov_b32_e32 v96, v236
	v_mov_b32_e32 v97, v237
	v_mov_b32_e32 v98, v238
	v_mov_b32_e32 v99, v239
	v_add_u32_e32 v202, 0x90, v144
	v_ashrrev_i32_e32 v203, 31, v202
	v_lshlrev_b64 v[202:203], 8, v[202:203]
	v_lshl_add_u64 v[202:203], v[138:139], 0, v[202:203]
	global_load_dwordx4 v[224:227], v[202:203], off offset:32
	global_load_dwordx4 v[228:231], v[202:203], off offset:48
	global_load_dwordx4 v[232:235], v[202:203], off
	global_load_dwordx4 v[236:239], v[202:203], off offset:16
	v_mov_b32_e32 v110, v93
	v_mov_b32_e32 v111, v95
	v_mov_b32_e32 v108, v85
	v_mov_b32_e32 v106, v97
	v_mov_b32_e32 v107, v99
	v_pk_mul_f32 v[88:89], v[104:105], v[106:107]
	v_mov_b32_e32 v109, v87
	v_mov_b32_e32 v97, v98
	v_mov_b32_e32 v85, v86
	v_pk_mul_f32 v[90:91], v[68:69], v[108:109]
	v_pk_fma_f32 v[88:89], v[78:79], v[96:97], v[88:89] neg_lo:[0,0,1] neg_hi:[0,0,1]
	v_pk_mul_f32 v[86:87], v[104:105], v[96:97]
	v_pk_mul_f32 v[96:97], v[68:69], v[84:85]
	v_pk_fma_f32 v[90:91], v[76:77], v[84:85], v[90:91] neg_lo:[0,0,1] neg_hi:[0,0,1]
	v_pk_fma_f32 v[84:85], v[78:79], v[106:107], v[86:87]
	v_pk_fma_f32 v[86:87], v[76:77], v[108:109], v[96:97]
	v_pk_mul_f32 v[106:107], v[66:67], v[80:81]
	v_mov_b32_e32 v108, v101
	v_mov_b32_e32 v109, v103
	v_pk_mul_f32 v[104:105], v[74:75], v[80:81]
	v_pk_mul_f32 v[96:97], v[106:107], v[108:109]
	v_mov_b32_e32 v101, v102
	v_mov_b32_e32 v93, v94
	v_pk_mul_f32 v[98:99], v[64:65], v[110:111]
	v_pk_fma_f32 v[96:97], v[104:105], v[100:101], v[96:97] neg_lo:[0,0,1] neg_hi:[0,0,1]
	v_pk_mul_f32 v[94:95], v[106:107], v[100:101]
	v_pk_mul_f32 v[100:101], v[64:65], v[92:93]
	v_pk_fma_f32 v[98:99], v[72:73], v[92:93], v[98:99] neg_lo:[0,0,1] neg_hi:[0,0,1]
	v_pk_fma_f32 v[92:93], v[104:105], v[108:109], v[94:95]
	v_pk_fma_f32 v[94:95], v[72:73], v[110:111], v[100:101]
	v_mov_b64_e32 v[100:101], s[20:21]
	v_mad_i64_i32 v[100:101], s[10:11], v82, s50, v[100:101]
	v_lshl_add_u64 v[100:101], s[0:1], 1, v[100:101]
	v_lshl_add_u64 v[104:105], v[100:101], 0, v[180:181]
	v_cvt_pk_bf16_f32 v100, v90, v91
	v_cvt_pk_bf16_f32 v101, v88, v89
	v_cvt_pk_bf16_f32 v102, v98, v99
	v_cvt_pk_bf16_f32 v103, v96, v97
	v_cvt_pk_bf16_f32 v86, v86, v87
	v_cvt_pk_bf16_f32 v87, v84, v85
	v_cvt_pk_bf16_f32 v88, v94, v95
	v_cvt_pk_bf16_f32 v89, v92, v93
	s_mov_b64 s[10:11], 0
	global_store_dwordx4 v[104:105], v[100:103], off offset:256
	global_store_dwordx4 v[104:105], v[86:89], off offset:320

.LBB0_863:
	v_mul_f32_e32 v64, 0x3dd53b94, v170
	s_nop 0
	v_add_u32_e32 v66, 0x80, v144
	v_mov_b32_e32 v65, v64
	v_pk_mul_f32 v[62:63], v[62:63], v[64:65] op_sel_hi:[1,0]
	v_pk_mul_f32 v[60:61], v[60:61], v[64:65] op_sel_hi:[1,0]
	v_ashrrev_i32_e32 v67, 31, v66
	s_mov_b64 s[10:11], -1
	s_and_b64 vcc, exec, s[42:43]
	v_pk_mul_f32 v[52:53], v[52:53], v[64:65]
	v_pk_mul_f32 v[56:57], v[56:57], v[64:65]
	v_pk_mul_f32 v[48:49], v[48:49], v[64:65]
	s_cbranch_vccnz .LBB0_865
	v_lshlrev_b64 v[68:69], 8, v[66:67]
	v_lshl_add_u64 v[72:73], v[138:139], 0, v[68:69]
	v_mov_b32_e32 v65, v64
	v_pk_mul_f32 v[88:89], v[54:55], v[64:65]
	s_waitcnt vmcnt(8)
	v_mov_b32_e32 v76, v206
	v_mov_b32_e32 v77, v207
	v_mov_b32_e32 v78, v208
	v_mov_b32_e32 v79, v209
	v_mov_b32_e32 v84, v210
	v_mov_b32_e32 v85, v211
	v_mov_b32_e32 v86, v212
	v_mov_b32_e32 v87, v213
	v_mov_b32_e32 v68, v214
	v_mov_b32_e32 v69, v215
	v_mov_b32_e32 v70, v216
	v_mov_b32_e32 v71, v217
	v_mov_b32_e32 v80, v220
	v_mov_b32_e32 v81, v221
	v_mov_b32_e32 v82, v222
	v_mov_b32_e32 v83, v223
	v_add_u32_e32 v202, 0xa0, v144
	v_ashrrev_i32_e32 v203, 31, v202
	v_lshlrev_b64 v[202:203], 8, v[202:203]
	v_lshl_add_u64 v[202:203], v[138:139], 0, v[202:203]
	global_load_dwordx4 v[206:209], v[202:203], off offset:32
	global_load_dwordx4 v[210:213], v[202:203], off offset:48
	global_load_dwordx4 v[214:217], v[202:203], off
	global_load_dwordx4 v[220:223], v[202:203], off offset:16
	v_mov_b32_e32 v94, v77
	v_mov_b32_e32 v95, v79
	v_mov_b32_e32 v92, v69
	v_mov_b32_e32 v90, v81
	v_mov_b32_e32 v91, v83
	v_pk_mul_f32 v[72:73], v[88:89], v[90:91]
	v_mov_b32_e32 v93, v71
	v_mov_b32_e32 v81, v82
	v_mov_b32_e32 v69, v70
	v_pk_mul_f32 v[74:75], v[52:53], v[92:93]
	v_pk_fma_f32 v[72:73], v[62:63], v[80:81], v[72:73] neg_lo:[0,0,1] neg_hi:[0,0,1]
	v_pk_mul_f32 v[70:71], v[88:89], v[80:81]
	v_pk_mul_f32 v[80:81], v[52:53], v[68:69]
	v_pk_fma_f32 v[74:75], v[60:61], v[68:69], v[74:75] neg_lo:[0,0,1] neg_hi:[0,0,1]
	v_pk_fma_f32 v[68:69], v[62:63], v[90:91], v[70:71]
	v_pk_fma_f32 v[70:71], v[60:61], v[92:93], v[80:81]
	v_pk_mul_f32 v[90:91], v[50:51], v[64:65]
	v_mov_b32_e32 v92, v85
	v_mov_b32_e32 v93, v87
	v_pk_mul_f32 v[88:89], v[58:59], v[64:65]
	v_pk_mul_f32 v[80:81], v[90:91], v[92:93]
	v_mov_b32_e32 v85, v86
	v_mov_b32_e32 v77, v78
	v_pk_mul_f32 v[82:83], v[48:49], v[94:95]
	v_pk_fma_f32 v[80:81], v[88:89], v[84:85], v[80:81] neg_lo:[0,0,1] neg_hi:[0,0,1]
	v_pk_mul_f32 v[78:79], v[90:91], v[84:85]
	v_pk_mul_f32 v[84:85], v[48:49], v[76:77]
	v_pk_fma_f32 v[82:83], v[56:57], v[76:77], v[82:83] neg_lo:[0,0,1] neg_hi:[0,0,1]
	v_pk_fma_f32 v[76:77], v[88:89], v[92:93], v[78:79]
	v_pk_fma_f32 v[78:79], v[56:57], v[94:95], v[84:85]
	v_mov_b64_e32 v[84:85], s[20:21]
	v_mad_i64_i32 v[84:85], s[10:11], v66, s50, v[84:85]
	v_lshl_add_u64 v[84:85], s[0:1], 1, v[84:85]
	v_lshl_add_u64 v[88:89], v[84:85], 0, v[180:181]
	v_cvt_pk_bf16_f32 v84, v74, v75
	v_cvt_pk_bf16_f32 v85, v72, v73
	v_cvt_pk_bf16_f32 v86, v82, v83
	v_cvt_pk_bf16_f32 v87, v80, v81
	v_cvt_pk_bf16_f32 v70, v70, v71
	v_cvt_pk_bf16_f32 v71, v68, v69
	v_cvt_pk_bf16_f32 v72, v78, v79
	v_cvt_pk_bf16_f32 v73, v76, v77
	s_mov_b64 s[10:11], 0
	global_store_dwordx4 v[88:89], v[84:87], off offset:256
	global_store_dwordx4 v[88:89], v[70:73], off offset:320

.LBB0_867:
	v_mul_f32_e32 v48, 0x3dd53b94, v169
	s_nop 0
	v_add_u32_e32 v50, 0x90, v144
	v_mov_b32_e32 v49, v48
	v_pk_mul_f32 v[46:47], v[46:47], v[48:49] op_sel_hi:[1,0]
	v_pk_mul_f32 v[44:45], v[44:45], v[48:49] op_sel_hi:[1,0]
	v_ashrrev_i32_e32 v51, 31, v50
	s_mov_b64 s[10:11], -1
	s_and_b64 vcc, exec, s[42:43]
	v_pk_mul_f32 v[36:37], v[36:37], v[48:49]
	v_pk_mul_f32 v[40:41], v[40:41], v[48:49]
	v_pk_mul_f32 v[32:33], v[32:33], v[48:49]
	s_cbranch_vccnz .LBB0_869
	v_lshlrev_b64 v[52:53], 8, v[50:51]
	v_lshl_add_u64 v[56:57], v[138:139], 0, v[52:53]
	v_mov_b32_e32 v49, v48
	v_pk_mul_f32 v[72:73], v[38:39], v[48:49]
	s_waitcnt vmcnt(8)
	v_mov_b32_e32 v60, v224
	v_mov_b32_e32 v61, v225
	v_mov_b32_e32 v62, v226
	v_mov_b32_e32 v63, v227
	v_mov_b32_e32 v68, v228
	v_mov_b32_e32 v69, v229
	v_mov_b32_e32 v70, v230
	v_mov_b32_e32 v71, v231
	v_mov_b32_e32 v52, v232
	v_mov_b32_e32 v53, v233
	v_mov_b32_e32 v54, v234
	v_mov_b32_e32 v55, v235
	v_mov_b32_e32 v64, v236
	v_mov_b32_e32 v65, v237
	v_mov_b32_e32 v66, v238
	v_mov_b32_e32 v67, v239
	v_add_u32_e32 v202, 0xb0, v144
	v_ashrrev_i32_e32 v203, 31, v202
	v_lshlrev_b64 v[202:203], 8, v[202:203]
	v_lshl_add_u64 v[202:203], v[138:139], 0, v[202:203]
	global_load_dwordx4 v[224:227], v[202:203], off offset:32
	global_load_dwordx4 v[228:231], v[202:203], off offset:48
	global_load_dwordx4 v[232:235], v[202:203], off
	global_load_dwordx4 v[236:239], v[202:203], off offset:16
	v_mov_b32_e32 v78, v61
	v_mov_b32_e32 v79, v63
	v_mov_b32_e32 v76, v53
	v_mov_b32_e32 v74, v65
	v_mov_b32_e32 v75, v67
	v_pk_mul_f32 v[56:57], v[72:73], v[74:75]
	v_mov_b32_e32 v77, v55
	v_mov_b32_e32 v65, v66
	v_mov_b32_e32 v53, v54
	v_pk_mul_f32 v[58:59], v[36:37], v[76:77]
	v_pk_fma_f32 v[56:57], v[46:47], v[64:65], v[56:57] neg_lo:[0,0,1] neg_hi:[0,0,1]
	v_pk_mul_f32 v[54:55], v[72:73], v[64:65]
	v_pk_mul_f32 v[64:65], v[36:37], v[52:53]
	v_pk_fma_f32 v[58:59], v[44:45], v[52:53], v[58:59] neg_lo:[0,0,1] neg_hi:[0,0,1]
	v_pk_fma_f32 v[52:53], v[46:47], v[74:75], v[54:55]
	v_pk_fma_f32 v[54:55], v[44:45], v[76:77], v[64:65]
	v_pk_mul_f32 v[74:75], v[34:35], v[48:49]
	v_mov_b32_e32 v76, v69
	v_mov_b32_e32 v77, v71
	v_pk_mul_f32 v[72:73], v[42:43], v[48:49]
	v_pk_mul_f32 v[64:65], v[74:75], v[76:77]
	v_mov_b32_e32 v69, v70
	v_mov_b32_e32 v61, v62
	v_pk_mul_f32 v[66:67], v[32:33], v[78:79]
	v_pk_fma_f32 v[64:65], v[72:73], v[68:69], v[64:65] neg_lo:[0,0,1] neg_hi:[0,0,1]
	v_pk_mul_f32 v[62:63], v[74:75], v[68:69]
	v_pk_mul_f32 v[68:69], v[32:33], v[60:61]
	v_pk_fma_f32 v[66:67], v[40:41], v[60:61], v[66:67] neg_lo:[0,0,1] neg_hi:[0,0,1]
	v_pk_fma_f32 v[60:61], v[72:73], v[76:77], v[62:63]
	v_pk_fma_f32 v[62:63], v[40:41], v[78:79], v[68:69]
	v_mov_b64_e32 v[68:69], s[20:21]
	v_mad_i64_i32 v[68:69], s[10:11], v50, s50, v[68:69]
	v_lshl_add_u64 v[68:69], s[0:1], 1, v[68:69]
	v_lshl_add_u64 v[72:73], v[68:69], 0, v[180:181]
	v_cvt_pk_bf16_f32 v68, v58, v59
	v_cvt_pk_bf16_f32 v69, v56, v57
	v_cvt_pk_bf16_f32 v70, v66, v67
	v_cvt_pk_bf16_f32 v71, v64, v65
	v_cvt_pk_bf16_f32 v54, v54, v55
	v_cvt_pk_bf16_f32 v55, v52, v53
	v_cvt_pk_bf16_f32 v56, v62, v63
	v_cvt_pk_bf16_f32 v57, v60, v61
	s_mov_b64 s[10:11], 0
	global_store_dwordx4 v[72:73], v[68:71], off offset:256
	global_store_dwordx4 v[72:73], v[54:57], off offset:320

.LBB0_871:
	s_waitcnt lgkmcnt(1)
	v_mul_f32_e32 v32, 0x3dd53b94, v168
	v_add_u32_e32 v34, 0xa0, v144
	v_mov_b32_e32 v33, v32
	v_pk_mul_f32 v[30:31], v[30:31], v[32:33] op_sel_hi:[1,0]
	v_pk_mul_f32 v[28:29], v[28:29], v[32:33] op_sel_hi:[1,0]
	v_ashrrev_i32_e32 v35, 31, v34
	s_mov_b64 s[10:11], -1
	s_and_b64 vcc, exec, s[42:43]
	v_pk_mul_f32 v[20:21], v[20:21], v[32:33]
	v_pk_mul_f32 v[24:25], v[24:25], v[32:33]
	v_pk_mul_f32 v[16:17], v[16:17], v[32:33]
	s_cbranch_vccnz .LBB0_873
	v_lshlrev_b64 v[36:37], 8, v[34:35]
	v_lshl_add_u64 v[40:41], v[138:139], 0, v[36:37]
	v_mov_b32_e32 v33, v32
	v_pk_mul_f32 v[56:57], v[22:23], v[32:33]
	s_waitcnt vmcnt(8)
	v_mov_b32_e32 v44, v206
	v_mov_b32_e32 v45, v207
	v_mov_b32_e32 v46, v208
	v_mov_b32_e32 v47, v209
	v_mov_b32_e32 v52, v210
	v_mov_b32_e32 v53, v211
	v_mov_b32_e32 v54, v212
	v_mov_b32_e32 v55, v213
	v_mov_b32_e32 v36, v214
	v_mov_b32_e32 v37, v215
	v_mov_b32_e32 v38, v216
	v_mov_b32_e32 v39, v217
	v_mov_b32_e32 v48, v220
	v_mov_b32_e32 v49, v221
	v_mov_b32_e32 v50, v222
	v_mov_b32_e32 v51, v223
	v_mov_b32_e32 v62, v45
	v_mov_b32_e32 v63, v47
	v_mov_b32_e32 v60, v37
	v_mov_b32_e32 v58, v49
	v_mov_b32_e32 v59, v51
	v_pk_mul_f32 v[40:41], v[56:57], v[58:59]
	v_mov_b32_e32 v61, v39
	v_mov_b32_e32 v49, v50
	v_mov_b32_e32 v37, v38
	v_pk_mul_f32 v[42:43], v[20:21], v[60:61]
	v_pk_fma_f32 v[40:41], v[30:31], v[48:49], v[40:41] neg_lo:[0,0,1] neg_hi:[0,0,1]
	v_pk_mul_f32 v[38:39], v[56:57], v[48:49]
	v_pk_mul_f32 v[48:49], v[20:21], v[36:37]
	v_pk_fma_f32 v[42:43], v[28:29], v[36:37], v[42:43] neg_lo:[0,0,1] neg_hi:[0,0,1]
	v_pk_fma_f32 v[36:37], v[30:31], v[58:59], v[38:39]
	v_pk_fma_f32 v[38:39], v[28:29], v[60:61], v[48:49]
	v_pk_mul_f32 v[58:59], v[18:19], v[32:33]
	v_mov_b32_e32 v60, v53
	v_mov_b32_e32 v61, v55
	v_pk_mul_f32 v[56:57], v[26:27], v[32:33]
	v_pk_mul_f32 v[48:49], v[58:59], v[60:61]
	v_mov_b32_e32 v53, v54
	v_mov_b32_e32 v45, v46
	v_pk_mul_f32 v[50:51], v[16:17], v[62:63]
	v_pk_fma_f32 v[48:49], v[56:57], v[52:53], v[48:49] neg_lo:[0,0,1] neg_hi:[0,0,1]
	v_pk_mul_f32 v[46:47], v[58:59], v[52:53]
	v_pk_mul_f32 v[52:53], v[16:17], v[44:45]
	v_pk_fma_f32 v[50:51], v[24:25], v[44:45], v[50:51] neg_lo:[0,0,1] neg_hi:[0,0,1]
	v_pk_fma_f32 v[44:45], v[56:57], v[60:61], v[46:47]
	v_pk_fma_f32 v[46:47], v[24:25], v[62:63], v[52:53]
	v_mov_b64_e32 v[52:53], s[20:21]
	v_mad_i64_i32 v[52:53], s[10:11], v34, s50, v[52:53]
	v_lshl_add_u64 v[52:53], s[0:1], 1, v[52:53]
	v_lshl_add_u64 v[56:57], v[52:53], 0, v[180:181]
	v_cvt_pk_bf16_f32 v52, v42, v43
	v_cvt_pk_bf16_f32 v53, v40, v41
	v_cvt_pk_bf16_f32 v54, v50, v51
	v_cvt_pk_bf16_f32 v55, v48, v49
	v_cvt_pk_bf16_f32 v38, v38, v39
	v_cvt_pk_bf16_f32 v39, v36, v37
	v_cvt_pk_bf16_f32 v40, v46, v47
	v_cvt_pk_bf16_f32 v41, v44, v45
	s_mov_b64 s[10:11], 0
	global_store_dwordx4 v[56:57], v[52:55], off offset:256
	global_store_dwordx4 v[56:57], v[38:41], off offset:320

.LBB0_878:
	v_lshlrev_b64 v[20:21], 8, v[18:19]
	v_lshl_add_u64 v[24:25], v[138:139], 0, v[20:21]
	v_mov_b32_e32 v17, v16
	v_pk_mul_f32 v[40:41], v[6:7], v[16:17]
	s_waitcnt vmcnt(4)
	v_mov_b32_e32 v28, v224
	v_mov_b32_e32 v29, v225
	v_mov_b32_e32 v30, v226
	v_mov_b32_e32 v31, v227
	v_mov_b32_e32 v36, v228
	v_mov_b32_e32 v37, v229
	v_mov_b32_e32 v38, v230
	v_mov_b32_e32 v39, v231
	v_mov_b32_e32 v20, v232
	v_mov_b32_e32 v21, v233
	v_mov_b32_e32 v22, v234
	v_mov_b32_e32 v23, v235
	v_mov_b32_e32 v32, v236
	v_mov_b32_e32 v33, v237
	v_mov_b32_e32 v34, v238
	v_mov_b32_e32 v35, v239
	v_mov_b32_e32 v46, v29
	v_mov_b32_e32 v47, v31
	v_mov_b32_e32 v44, v21
	v_mov_b32_e32 v42, v33
	v_mov_b32_e32 v43, v35
	v_pk_mul_f32 v[24:25], v[40:41], v[42:43]
	v_mov_b32_e32 v45, v23
	v_mov_b32_e32 v33, v34
	v_mov_b32_e32 v21, v22
	v_pk_mul_f32 v[26:27], v[4:5], v[44:45]
	v_pk_fma_f32 v[24:25], v[14:15], v[32:33], v[24:25] neg_lo:[0,0,1] neg_hi:[0,0,1]
	v_pk_mul_f32 v[22:23], v[40:41], v[32:33]
	v_pk_mul_f32 v[32:33], v[4:5], v[20:21]
	v_pk_fma_f32 v[26:27], v[12:13], v[20:21], v[26:27] neg_lo:[0,0,1] neg_hi:[0,0,1]
	v_pk_fma_f32 v[20:21], v[14:15], v[42:43], v[22:23]
	v_pk_fma_f32 v[22:23], v[12:13], v[44:45], v[32:33]
	v_pk_mul_f32 v[42:43], v[2:3], v[16:17]
	v_mov_b32_e32 v44, v37
	v_mov_b32_e32 v45, v39
	v_pk_mul_f32 v[40:41], v[10:11], v[16:17]
	v_pk_mul_f32 v[32:33], v[42:43], v[44:45]
	v_mov_b32_e32 v37, v38
	v_mov_b32_e32 v29, v30
	v_pk_mul_f32 v[34:35], v[0:1], v[46:47]
	v_pk_fma_f32 v[32:33], v[40:41], v[36:37], v[32:33] neg_lo:[0,0,1] neg_hi:[0,0,1]
	v_pk_mul_f32 v[30:31], v[42:43], v[36:37]
	v_pk_mul_f32 v[36:37], v[0:1], v[28:29]
	v_pk_fma_f32 v[34:35], v[8:9], v[28:29], v[34:35] neg_lo:[0,0,1] neg_hi:[0,0,1]
	v_pk_fma_f32 v[28:29], v[40:41], v[44:45], v[30:31]
	v_pk_fma_f32 v[30:31], v[8:9], v[46:47], v[36:37]
	v_mov_b64_e32 v[36:37], s[20:21]
	v_mad_i64_i32 v[36:37], s[10:11], v18, s50, v[36:37]
	v_lshl_add_u64 v[36:37], s[0:1], 1, v[36:37]
	v_lshl_add_u64 v[40:41], v[36:37], 0, v[180:181]
	v_cvt_pk_bf16_f32 v36, v26, v27
	v_cvt_pk_bf16_f32 v37, v24, v25
	v_cvt_pk_bf16_f32 v38, v34, v35
	v_cvt_pk_bf16_f32 v39, v32, v33
	v_cvt_pk_bf16_f32 v22, v22, v23
	v_cvt_pk_bf16_f32 v23, v20, v21
	v_cvt_pk_bf16_f32 v24, v30, v31
	v_cvt_pk_bf16_f32 v25, v28, v29
	global_store_dwordx4 v[40:41], v[36:39], off offset:256
	global_store_dwordx4 v[40:41], v[22:25], off offset:320
	s_cbranch_execnz .LBB0_877
